# baseline (speedup 1.0000x reference)
; template <int MODE>
; __device__ __forceinline__ void attn_item(const Params& P, int b, int h, int qb, char* lds) {
;     ...
;         const float nref = -m_reg;
; #pragma unroll
;         for (int r = 0; r < 16; ++r) { p0[r] = nref; p1[r] = nref; }
;       }
;       {
;         const char* kbp = K_lds + buf * 16384;
; #pragma unroll
;         for (int d0 = 0; d0 < 8; ++d0) {
;           const char* a = kbp + KSWZ(r32, (d0 * 16 + hi * 8) * 2);
;           const bf16x8 b0 = *(const bf16x8*)a;
;           const bf16x8 b1 = *(const bf16x8*)(a + 32 * 256);
;           p0 = __builtin_amdgcn_mfma_f32_32x32x16_bf16(b0, qr[d0], p0, 0, 0, 0);
;           p1 = __builtin_amdgcn_mfma_f32_32x32x16_bf16(b1, qr[d0], p1, 0, 0, 0);
;         }
;       }
;       const float NEG = -__builtin_inff();
;       if (MODE == 0) {
;       } else {
;         if (kb + 63 > q0) {
;           const int dq = qpos - kb - 4 * hi;
; #pragma unroll
;           for (int r = 0; r < 16; ++r) {
;             const int c = (r & 3) + 8 * (r >> 2);
;             if (dq - c < 0) p0[r] = NEG;
;             if (dq - c - 32 < 0) p1[r] = NEG;
;           }
;         }
;       }
;       float pmax = p0[0];
; #pragma unroll
;       for (int r = 1; r < 16; ++r) pmax = fmaxf(pmax, p0[r]);
; #pragma unroll
;       for (int r = 0; r < 16; ++r) pmax = fmaxf(pmax, p1[r]);
;       pmax = fmaxf(pmax, __shfl_xor(pmax, 32));
;       if (!(started && __all(pmax < -160.f))) {
;       float alpha = 1.f;
;       if (!started || __any(pmax > 6.f)) {
.Lmy_pr_a:
	v_add_u32_e32 v0, s9, v182
	v_add_u32_e32 v6, v0, v183
	v_add_u32_e32 v10, v0, v181
	ds_read_b128 v[212:215], v6 offset:32768
	ds_read_b128 v[6:9], v6 offset:40960
	v_add_u32_e32 v187, v0, v179
	ds_read_b128 v[216:219], v10 offset:32768
	ds_read_b128 v[10:13], v10 offset:40960
	v_add_u32_e32 v2, v0, v178
	ds_read_b128 v[220:223], v187 offset:32768
	ds_read_b128 v[188:191], v187 offset:40960
	v_add_u32_e32 v196, v0, v177
	ds_read_b128 v[224:227], v2 offset:32768
	ds_read_b128 v[192:195], v2 offset:40960
	v_add_u32_e32 v3, v0, v176
	ds_read_b128 v[228:231], v196 offset:32768
	ds_read_b128 v[196:199], v196 offset:40960
	v_add_u32_e32 v204, v0, v175
	ds_read_b128 v[232:235], v3 offset:32768
	ds_read_b128 v[200:203], v3 offset:40960
	ds_read_b128 v[236:239], v204 offset:32768
	ds_read_b128 v[204:207], v204 offset:40960
	v_add_u32_e32 v0, v0, v174
	v_xor_b32_e32 v96, 0x80000000, v186
	v_mov_b32_e32 v97, v96
	v_mov_b64_e32 v[98:99], v[96:97]
	v_mov_b64_e32 v[100:101], v[96:97]
	v_mov_b64_e32 v[102:103], v[96:97]
	v_mov_b64_e32 v[104:105], v[96:97]
	v_mov_b64_e32 v[106:107], v[96:97]
	v_mov_b64_e32 v[108:109], v[96:97]
	v_mov_b64_e32 v[110:111], v[96:97]
	s_cmp_eq_u32 s0, 0
	s_cselect_b64 s[10:11], -1, 0
	s_cmp_lg_u32 s0, 0
	s_waitcnt lgkmcnt(13)
	v_mfma_f32_32x32x16_bf16 v[112:127], v[212:215], v[156:159], v[96:111]
	ds_read_b128 v[240:243], v0 offset:32768
	ds_read_b128 v[208:211], v0 offset:40960
	s_waitcnt lgkmcnt(14)
	v_mfma_f32_32x32x16_bf16 v[96:111], v[6:9], v[156:159], v[96:111]
	s_waitcnt lgkmcnt(12)
	v_mfma_f32_32x32x16_bf16 v[112:127], v[216:219], v[152:155], v[112:127]
	v_mfma_f32_32x32x16_bf16 v[96:111], v[10:13], v[152:155], v[96:111]
	s_waitcnt lgkmcnt(10)
	v_mfma_f32_32x32x16_bf16 v[112:127], v[220:223], v[148:151], v[112:127]
	v_mfma_f32_32x32x16_bf16 v[96:111], v[188:191], v[148:151], v[96:111]
	s_waitcnt lgkmcnt(8)
	v_mfma_f32_32x32x16_bf16 v[112:127], v[224:227], v[144:147], v[112:127]
	v_mfma_f32_32x32x16_bf16 v[96:111], v[192:195], v[144:147], v[96:111]
	s_waitcnt lgkmcnt(6)
	v_mfma_f32_32x32x16_bf16 v[112:127], v[228:231], v[140:143], v[112:127]
	v_mfma_f32_32x32x16_bf16 v[96:111], v[196:199], v[140:143], v[96:111]
	s_waitcnt lgkmcnt(4)
	v_mfma_f32_32x32x16_bf16 v[112:127], v[232:235], v[136:139], v[112:127]
	v_mfma_f32_32x32x16_bf16 v[96:111], v[200:203], v[136:139], v[96:111]
	s_waitcnt lgkmcnt(2)
	v_mfma_f32_32x32x16_bf16 v[112:127], v[236:239], v[132:135], v[112:127]
	v_mfma_f32_32x32x16_bf16 v[96:111], v[204:207], v[132:135], v[96:111]
	s_waitcnt lgkmcnt(0)
	v_mfma_f32_32x32x16_bf16 v[112:127], v[240:243], v[128:131], v[112:127]
	v_mfma_f32_32x32x16_bf16 v[96:111], v[208:211], v[128:131], v[96:111]
	s_nop 10
	v_max_f32_e32 v0, v113, v113
	v_max_f32_e32 v2, v112, v112
	v_max_f32_e32 v0, v2, v0
	v_max3_f32 v0, v0, v114, v115
	v_max3_f32 v0, v0, v116, v117
	v_max3_f32 v0, v0, v118, v119
	v_max3_f32 v0, v0, v120, v121
	v_max3_f32 v0, v0, v122, v123
	v_max3_f32 v0, v0, v124, v125
	v_max3_f32 v0, v0, v126, v127
	v_max3_f32 v0, v0, v96, v97
	v_max3_f32 v0, v0, v98, v99
	v_max3_f32 v0, v0, v100, v101
	v_max3_f32 v0, v0, v102, v103
	v_max3_f32 v0, v0, v104, v105
	v_max3_f32 v0, v0, v106, v107
	v_max3_f32 v0, v0, v108, v109
	v_max3_f32 v0, v0, v110, v111
	v_mov_b32_e32 v2, v0
	s_nop 1
	v_permlane32_swap_b32_e32 v0, v2
	v_max_f32_e32 v0, v0, v2
	s_cbranch_scc0 .LBB0_689
	v_cmp_gt_f32_e32 vcc, s45, v0
	s_mov_b64 s[36:37], 0
	s_cmp_lg_u64 vcc, exec
	s_mov_b64 s[34:35], 0
	s_mov_b64 s[38:39], 0
	s_cbranch_scc0 .LBB0_690
	v_cmp_lt_f32_e32 vcc, s46, v0
	s_cbranch_vccz .Lmy_fast0
	v_max_f32_e32 v2, v0, v0
	v_max_f32_e32 v2, 0, v2
	s_mov_b64 s[38:39], -1
	s_and_b64 vcc, exec, s[36:37]
	s_cbranch_vccnz .LBB0_691
